# v24 + one static priority raise for waves 4-7 during the FFT phases (vx, conv), reset after conv
# baseline (speedup 1.0000x reference)
; DI void phase_vx(const Params& p, int ch) {
;   int tix_ = threadIdx.x; asm volatile("" : "+v"(tix_));
;   const bft* Z = (const bft*)(p.ws + OFF_U); bft* vxT = (bft*)(p.ws + OFF_VXT);
;   const float* kraw = (const float*)(p.ws + OFF_KRAW); float2* khat = (float2*)(p.ws + OFF_KHAT);
;   const int tid = tix_; float* tile = (float*)smem;
;   const float* cw = p.hy_conv_w; const float* cb = p.hy_conv_b;
;   for (int it = blockIdx.x; it < 512; it += gridDim.x) {
;     int cc = it & 255;
;     if (it < 256) filtfft_item<14>(p, ch, cc, kraw + (size_t)cc * 16384, khat + (size_t)cc * 16384);
;     else filtfft_item<13>(p, ch, cc, kraw + (size_t)16384 * 256 + (size_t)cc * 8192, khat + (size_t)16384 * 256 + (size_t)cc * 8192);
;   }
.LBB0_1465:
	s_or_b64 exec, exec, s[0:1]
	v_readlane_b32 s0, v240, 38
	v_readlane_b32 s1, v240, 39
	s_andn2_b64 vcc, exec, s[0:1]
	v_readlane_b32 s0, v240, 10
	v_mov_b32_e32 v91, v180
	s_lshl_b32 s75, s36, 8
	s_mov_b32 s14, s0
	s_mov_b32 s15, s0
	s_waitcnt lgkmcnt(0)
	s_barrier
	v_readfirstlane_b32 s98, v180
	s_cmp_ge_u32 s98, 0x100
	s_cbranch_scc0 .Lprio_skip_vx
	s_setprio 2
.Lprio_skip_vx:
	v_readlane_b32 s1, v240, 11
	s_cbranch_vccz .LBB0_1481

; DI void phase_gate(const Params& p, int ch) {
;   int tix_ = threadIdx.x; asm volatile("" : "+v"(tix_));
;   const bft* Z = (const bft*)(p.ws + OFF_U); const bft* yT = (const bft*)(p.ws + OFF_VXT); bft* G1 = (bft*)(p.ws + OFF_G1H) + (ch & 3) * 256;
;   const int tid = tix_; float* tile = (float*)smem;
;   const float* cw = p.hy_conv_w; const float* cb = p.hy_conv_b;
;   float w0[3][8], b0[8];
;   { const int c0 = ch * 256 + (tid & 31) * 8;
; #pragma unroll
;     for (int i = 0; i < 8; ++i) { b0[i] = cb[c0 + i];
; #pragma unroll
;       for (int t = 0; t < 3; ++t) w0[t][i] = cw[t * 6144 + c0 + i]; } }
;   for (int it = blockIdx.x; it < T / 64; it += gridDim.x) {
;     const int tok0 = it * 64;
;     { int cl = tid >> 1, th = (tid & 1) * 32; const bft* s = yT + (size_t)cl * T + tok0 + th;
; #pragma unroll
;       for (int q = 0; q < 4; ++q) { u32x4 v = *(const u32x4*)(s + q * 8);
; #pragma unroll
;         for (int k = 0; k < 4; ++k) { tile[cl * 65 + th + q * 8 + 2 * k] = __uint_as_float(v[k] << 16); tile[cl * 65 + th + q * 8 + 2 * k + 1] = __uint_as_float(v[k] & 0xffff0000u); } } }
.LBB0_1706:
	s_or_b64 exec, exec, s[0:1]
	v_mov_b32_e32 v45, v180
	s_and_b64 vcc, exec, s[8:9]
	s_waitcnt lgkmcnt(0)
	s_barrier
	s_setprio 0
	s_cbranch_vccnz .LBB0_1715
	v_lshlrev_b32_e32 v0, 3, v45
	v_and_b32_e32 v44, 0xf8, v0
	v_or_b32_e32 v0, s75, v44
	v_readlane_b32 s8, v240, 49
	v_lshlrev_b64 v[6:7], 2, v[0:1]
	v_readlane_b32 s9, v240, 50
	s_movk_i32 s0, 0x6000
	v_readlane_b32 s10, v240, 51
	v_lshl_add_u64 v[30:31], s[8:9], 0, v[6:7]
	v_add_co_u32_e32 v18, vcc, s0, v30
	s_mov_b32 s0, 0xc000
	s_nop 0
	v_addc_co_u32_e32 v19, vcc, 0, v31, vcc
	v_readlane_b32 s11, v240, 52
	v_add_co_u32_e32 v22, vcc, s0, v30
	s_mov_b64 s[0:1], 0x6000
	v_lshl_add_u64 v[10:11], s[10:11], 0, v[6:7]
	v_lshl_add_u64 v[26:27], v[30:31], 0, s[0:1]
	s_mov_b64 s[0:1], 0xc000
	global_load_dwordx4 v[2:5], v[10:11], off
	global_load_dwordx4 v[6:9], v[30:31], off
	s_nop 0
	global_load_dwordx4 v[10:13], v[10:11], off offset:16
	s_nop 0
	global_load_dwordx4 v[14:17], v[30:31], off offset:16
	v_addc_co_u32_e32 v23, vcc, 0, v31, vcc
	v_lshl_add_u64 v[30:31], v[30:31], 0, s[0:1]
	global_load_dwordx4 v[18:21], v[18:19], off
	s_and_b32 s0, s75, 0x300
	global_load_dwordx4 v[22:25], v[22:23], off
	v_ashrrev_i32_e32 v0, 1, v45
	global_load_dwordx4 v[26:29], v[26:27], off offset:16
	v_mov_b64_e32 v[34:35], s[82:83]
	global_load_dwordx4 v[30:33], v[30:31], off offset:16
	s_lshl_b32 s8, s0, 1
	s_mov_b32 s0, 0x18000
	v_lshlrev_b32_e32 v36, 5, v45
	v_mad_i64_i32 v[34:35], s[0:1], v0, s0, v[34:35]
	v_and_b32_e32 v36, 32, v36
	s_movk_i32 s1, 0x104
	v_mul_lo_u32 v37, v0, s1
	s_add_u32 s0, s68, s8
	v_lshlrev_b32_e32 v0, 1, v36
	v_mad_u32_u24 v56, v44, s1, 16
	s_addc_u32 s1, s69, 0
	v_lshl_add_u64 v[46:47], v[34:35], 0, v[0:1]
	v_lshlrev_b32_e32 v0, 1, v44
	v_lshlrev_b32_e32 v38, 2, v36
	v_lshl_add_u64 v[48:49], s[0:1], 0, v[0:1]
	v_readlane_b32 s0, v240, 10
	v_add3_u32 v57, 16, v37, v38
	s_mov_b32 s10, s0
	v_readlane_b32 s1, v240, 11
	s_waitcnt vmcnt(6)
	v_mov_b32_e32 v52, v7
	v_mov_b32_e32 v50, v3
	v_mov_b32_e32 v51, v5
	v_mov_b32_e32 v53, v9
	v_mov_b32_e32 v3, v4
	v_mov_b32_e32 v7, v8
	s_waitcnt vmcnt(5)
	v_mov_b32_e32 v4, v11
	v_mov_b32_e32 v5, v13
	s_waitcnt vmcnt(4)
	v_mov_b32_e32 v8, v15
	v_mov_b32_e32 v9, v17
	v_mov_b32_e32 v11, v12
	v_mov_b32_e32 v15, v16
	s_waitcnt vmcnt(3)
	v_mov_b32_e32 v12, v19
	v_mov_b32_e32 v13, v21
	s_waitcnt vmcnt(2)
	v_mov_b32_e32 v16, v23
	v_mov_b32_e32 v17, v25
	v_mov_b32_e32 v19, v20
	v_mov_b32_e32 v23, v24
	s_waitcnt vmcnt(1)
	v_mov_b32_e32 v20, v27
	v_mov_b32_e32 v21, v29
	s_waitcnt vmcnt(0)
	v_mov_b32_e32 v24, v31
	v_mov_b32_e32 v25, v33
	v_mov_b32_e32 v27, v28
	v_mov_b32_e32 v31, v32
	s_branch .LBB0_1709

; #define LAS __attribute__((address_space(3)))
; __global__ void __launch_bounds__(NTHR) mega(Params p) {
;   cg::grid_group grid = cg::this_grid();
;   if (threadIdx.x == 0) xb_words = make_uint4(0u, 0u, 0u, 0u);
;   __syncthreads();
;   XcdBarrier xb = xcd_barrier_post((unsigned*)(p.ws + OFF_BAR), (volatile LAS unsigned*)&xb_words);
	.amdhsa_kernel _Z4mega6Params
		.amdhsa_group_segment_fixed_size 16
		.amdhsa_private_segment_fixed_size 0
		.amdhsa_kernarg_size 816
		.amdhsa_user_sgpr_count 2
		.amdhsa_user_sgpr_dispatch_ptr 0
		.amdhsa_user_sgpr_queue_ptr 0
		.amdhsa_user_sgpr_kernarg_segment_ptr 1
		.amdhsa_user_sgpr_dispatch_id 0
		.amdhsa_user_sgpr_kernarg_preload_length 0
		.amdhsa_user_sgpr_kernarg_preload_offset 0
		.amdhsa_user_sgpr_private_segment_size 0
		.amdhsa_uses_dynamic_stack 0
		.amdhsa_enable_private_segment 0
		.amdhsa_system_sgpr_workgroup_id_x 1
		.amdhsa_system_sgpr_workgroup_id_y 0
		.amdhsa_system_sgpr_workgroup_id_z 0
		.amdhsa_system_sgpr_workgroup_info 0
		.amdhsa_system_vgpr_workitem_id 2
		.amdhsa_next_free_vgpr 256
		.amdhsa_next_free_sgpr 99
		.amdhsa_accum_offset 256
		.amdhsa_reserve_vcc 1
		.amdhsa_float_round_mode_32 0
		.amdhsa_float_round_mode_16_64 0
		.amdhsa_float_denorm_mode_32 3
		.amdhsa_float_denorm_mode_16_64 3
		.amdhsa_dx10_clamp 1
		.amdhsa_ieee_mode 1
		.amdhsa_fp16_overflow 0
		.amdhsa_tg_split 0
		.amdhsa_exception_fp_ieee_invalid_op 0
		.amdhsa_exception_fp_denorm_src 0
		.amdhsa_exception_fp_ieee_div_zero 0
		.amdhsa_exception_fp_ieee_overflow 0
		.amdhsa_exception_fp_ieee_underflow 0
		.amdhsa_exception_fp_ieee_inexact 0
		.amdhsa_exception_int_div_zero 0
	.end_amdhsa_kernel

; #define LAS __attribute__((address_space(3)))
; __global__ void __launch_bounds__(NTHR) mega(Params p) {
;   cg::grid_group grid = cg::this_grid();
;   if (threadIdx.x == 0) xb_words = make_uint4(0u, 0u, 0u, 0u);
;   __syncthreads();
;   XcdBarrier xb = xcd_barrier_post((unsigned*)(p.ws + OFF_BAR), (volatile LAS unsigned*)&xb_words);
amdhsa.kernels:
  - .agpr_count:     0
    .args:
      - .offset:         0
        .size:           560
        .value_kind:     by_value
      - .offset:         560
        .size:           4
        .value_kind:     hidden_block_count_x
      - .offset:         564
        .size:           4
        .value_kind:     hidden_block_count_y
      - .offset:         568
        .size:           4
        .value_kind:     hidden_block_count_z
      - .offset:         572
        .size:           2
        .value_kind:     hidden_group_size_x
      - .offset:         574
        .size:           2
        .value_kind:     hidden_group_size_y
      - .offset:         576
        .size:           2
        .value_kind:     hidden_group_size_z
      - .offset:         578
        .size:           2
        .value_kind:     hidden_remainder_x
      - .offset:         580
        .size:           2
        .value_kind:     hidden_remainder_y
      - .offset:         582
        .size:           2
        .value_kind:     hidden_remainder_z
      - .offset:         600
        .size:           8
        .value_kind:     hidden_global_offset_x
      - .offset:         608
        .size:           8
        .value_kind:     hidden_global_offset_y
      - .offset:         616
        .size:           8
        .value_kind:     hidden_global_offset_z
      - .offset:         624
        .size:           2
        .value_kind:     hidden_grid_dims
      - .offset:         648
        .size:           8
        .value_kind:     hidden_multigrid_sync_arg
      - .offset:         680
        .size:           4
        .value_kind:     hidden_dynamic_lds_size
    .group_segment_fixed_size: 16
    .kernarg_segment_align: 8
    .kernarg_segment_size: 816
    .language:       OpenCL C
    .language_version:
      - 2
      - 0
    .max_flat_workgroup_size: 512
    .name:           _Z4mega6Params
    .private_segment_fixed_size: 0
    .sgpr_count:     105
    .sgpr_spill_count: 59
    .symbol:         _Z4mega6Params.kd
    .uniform_work_group_size: 1
    .uses_dynamic_stack: false
    .vgpr_count:     256
    .vgpr_spill_count: 0
    .wavefront_size: 64
